# v044 plus: final-phase bf16 stream copy (never read again) masked off, 32 MB fewer stores at the kernel tail
# speedup vs baseline: 1.0124x; 1.0084x over previous
; DI unsigned pk2(float lo, float hi) { f32x2 v = {lo, hi}; return __builtin_bit_cast(unsigned, __builtin_convertvector(v, bf2_t)); }
;     DI void fused(f32x4 (&acc)[2][2][4][2], const Unit& u, int wr, int wc, int fr, int fq, LAS unsigned char* lds, int wid, int lane) const {
;     ...
;         f32x4 gv[2][2], bv[2][2];
; #pragma unroll
;         for (int bj = 0; bj < 2; ++bj)
; #pragma unroll
;             for (int n = 0; n < 2; ++n) { gv[bj][n] = *(const f32x4*)(gam + col0 + bj * HALF + n * 4); bv[bj][n] = *(const f32x4*)(bet + col0 + bj * HALF + n * 4); }
; #pragma unroll
;         for (int ai = 0; ai < 2; ++ai)
; #pragma unroll
;             for (int m = 0; m < 4; ++m) {
;                 const int r = ai * HALF + wr * 64 + m * 16 + fr; const f32x2v sr = S[r]; const size_t off = (size_t)(u.pm * BM + r) * D + col0;
; #pragma unroll
;                 for (int bj = 0; bj < 2; ++bj) {
;                     const f32x4 o0 = (acc[ai][bj][m][0] - sr.x) * sr.y * gv[bj][0] + bv[bj][0], o1 = (acc[ai][bj][m][1] - sr.x) * sr.y * gv[bj][1] + bv[bj][1];
;                     if (Xo) { *(f32x4*)(Xo + off + bj * HALF) = o0; *(f32x4*)(Xo + off + bj * HALF + 4) = o1; }
;                     u32x4 w; w.x = pk2(o0[0], o0[1]); w.y = pk2(o0[2], o0[3]); w.z = pk2(o1[0], o1[1]); w.w = pk2(o1[2], o1[3]);
;                     *(u32x4*)(XB + off + bj * HALF) = w;
;                 }
;             }
.LBB0_195:
	s_or_b64 exec, exec, s[16:17]
	v_readlane_b32 s4, v255, 16
	v_readlane_b32 s5, v255, 17
	s_cmp_eq_u32 s33, 14
	s_mov_b32 s5, s72
	s_cselect_b32 s1, s91, 0
	s_cselect_b32 s0, s90, 0
	s_lshl_b64 s[4:5], s[4:5], 13
	s_add_u32 s6, s58, s4
	s_addc_u32 s7, s59, s5
	s_add_u32 s4, s60, s4
	s_addc_u32 s5, s61, s5
	v_lshlrev_b64 v[130:131], 2, v[164:165]
	s_waitcnt lgkmcnt(0)
	s_barrier
	v_lshl_add_u64 v[134:135], s[6:7], 0, v[130:131]
	v_lshl_add_u64 v[142:143], s[4:5], 0, v[130:131]
	global_load_dwordx4 v[146:149], v[134:135], off offset:16
	global_load_dwordx4 v[154:157], v[134:135], off
	global_load_dwordx4 v[158:161], v[142:143], off
	global_load_dwordx4 v[150:153], v[142:143], off offset:16
	global_load_dwordx4 v[130:133], v[134:135], off offset:528
	global_load_dwordx4 v[138:141], v[134:135], off offset:512
	s_nop 0
	global_load_dwordx4 v[134:137], v[142:143], off offset:528
	s_nop 0
	global_load_dwordx4 v[142:145], v[142:143], off offset:512
	v_lshl_add_u32 v96, v216, 3, 0
	ds_read_b64 v[184:185], v96 offset:8192
	v_add_u32_e32 v182, s12, v216
	v_ashrrev_i32_e32 v183, 31, v182
	v_lshlrev_b64 v[186:187], 11, v[182:183]
	v_lshl_add_u64 v[186:187], v[186:187], 0, v[164:165]
	s_waitcnt lgkmcnt(0)
	v_sub_f32_e32 v7, v7, v184
	v_sub_f32_e32 v6, v6, v184
	v_sub_f32_e32 v5, v5, v184
	v_sub_f32_e32 v4, v4, v184
	v_sub_f32_e32 v3, v3, v184
	v_sub_f32_e32 v2, v2, v184
	v_sub_f32_e32 v1, v1, v184
	v_sub_f32_e32 v0, v0, v184
	s_cmp_lg_u64 s[0:1], 0
	v_pk_mul_f32 v[4:5], v[184:185], v[4:5] op_sel:[1,0]
	v_pk_mul_f32 v[6:7], v[184:185], v[6:7] op_sel:[1,0]
	v_pk_mul_f32 v[192:193], v[184:185], v[0:1] op_sel:[1,0]
	v_pk_mul_f32 v[194:195], v[184:185], v[2:3] op_sel:[1,0]
	s_cselect_b64 s[16:17], -1, 0
	s_not_b64 s[100:101], s[16:17]
	s_cmp_eq_u64 s[0:1], 0
	v_lshl_add_u64 v[186:187], v[186:187], 2, s[0:1]
	s_waitcnt vmcnt(5)
	v_pk_fma_f32 v[2:3], v[156:157], v[6:7], v[160:161]
	v_pk_fma_f32 v[0:1], v[154:155], v[4:5], v[158:159]
	s_waitcnt vmcnt(4)
	v_pk_fma_f32 v[6:7], v[148:149], v[194:195], v[152:153]
	v_pk_fma_f32 v[4:5], v[146:147], v[192:193], v[150:151]
	s_cbranch_scc1 .LBB0_197
	global_store_dwordx4 v[186:187], v[0:3], off
	global_store_dwordx4 v[186:187], v[4:7], off offset:16
.LBB0_197:
	s_nop 0
	v_cvt_pk_bf16_f32 v0, v0, v1
	v_cvt_pk_bf16_f32 v1, v2, v3
	v_cvt_pk_bf16_f32 v2, v4, v5
	v_cvt_pk_bf16_f32 v3, v6, v7
	v_mov_b32_e32 v192, v185
	v_mov_b32_e32 v193, v185
	s_mov_b64 exec, s[100:101]
	global_store_dwordx4 v[166:167], v[0:3], off
	s_mov_b64 exec, -1
	v_mov_b32_e32 v6, v185
	v_mov_b32_e32 v7, v185
	v_sub_f32_e32 v1, v15, v184
	v_sub_f32_e32 v0, v14, v184
	v_sub_f32_e32 v3, v13, v184
	v_sub_f32_e32 v2, v12, v184
	v_pk_mul_f32 v[4:5], v[192:193], v[2:3]
	v_pk_mul_f32 v[0:1], v[6:7], v[0:1]
	v_sub_f32_e32 v9, v9, v184
	s_waitcnt vmcnt(1)
	v_pk_fma_f32 v[2:3], v[140:141], v[0:1], v[144:145]
	v_pk_fma_f32 v[0:1], v[138:139], v[4:5], v[142:143]
	v_sub_f32_e32 v5, v11, v184
	v_sub_f32_e32 v4, v10, v184
	v_sub_f32_e32 v8, v8, v184
	v_pk_mul_f32 v[4:5], v[6:7], v[4:5]
	v_pk_mul_f32 v[8:9], v[192:193], v[8:9]
	v_pk_fma_f32 v[6:7], v[132:133], v[4:5], v[136:137]
	v_cndmask_b32_e64 v4, 0, 1, s[16:17]
	v_cmp_ne_u32_e64 s[40:41], 1, v4
	s_andn2_b64 vcc, exec, s[16:17]
	v_pk_fma_f32 v[4:5], v[130:131], v[8:9], v[134:135]
	s_cbranch_vccnz .LBB0_199
	global_store_dwordx4 v[186:187], v[0:3], off offset:512
	global_store_dwordx4 v[186:187], v[4:7], off offset:528
.LBB0_199:
	ds_read_b64 v[8:9], v96 offset:8320
	v_cvt_pk_bf16_f32 v0, v0, v1
	v_cvt_pk_bf16_f32 v1, v2, v3
	v_cvt_pk_bf16_f32 v2, v4, v5
	v_cvt_pk_bf16_f32 v3, v6, v7
	s_mov_b64 exec, s[100:101]
	global_store_dwordx4 v[166:167], v[0:3], off offset:256
	s_mov_b64 exec, -1
	s_waitcnt lgkmcnt(0)
	v_sub_f32_e32 v7, v17, v8
	v_sub_f32_e32 v6, v16, v8
	v_add3_u32 v0, s12, v216, 16
	v_ashrrev_i32_e32 v1, 31, v0
	v_lshlrev_b64 v[0:1], 11, v[0:1]
	v_lshl_add_u64 v[10:11], v[0:1], 0, v[164:165]
	v_sub_f32_e32 v1, v23, v8
	v_sub_f32_e32 v0, v22, v8
	v_sub_f32_e32 v3, v21, v8
	v_sub_f32_e32 v2, v20, v8
	v_pk_mul_f32 v[4:5], v[8:9], v[2:3] op_sel:[1,0]
	v_pk_mul_f32 v[0:1], v[8:9], v[0:1] op_sel:[1,0]
	v_pk_mul_f32 v[12:13], v[8:9], v[6:7] op_sel:[1,0]
	v_pk_fma_f32 v[2:3], v[156:157], v[0:1], v[160:161]
	v_pk_fma_f32 v[0:1], v[154:155], v[4:5], v[158:159]
	v_sub_f32_e32 v5, v19, v8
	v_sub_f32_e32 v4, v18, v8
	v_pk_mul_f32 v[4:5], v[8:9], v[4:5] op_sel:[1,0]
	s_and_b64 vcc, exec, s[40:41]
	v_pk_fma_f32 v[6:7], v[148:149], v[4:5], v[152:153]
	v_pk_fma_f32 v[4:5], v[146:147], v[12:13], v[150:151]
	v_lshl_add_u64 v[10:11], v[10:11], 2, s[0:1]
	s_cbranch_vccnz .LBB0_201
	global_store_dwordx4 v[10:11], v[0:3], off
	global_store_dwordx4 v[10:11], v[4:7], off offset:16
.LBB0_201:
	s_nop 0
	v_cvt_pk_bf16_f32 v0, v0, v1
	v_cvt_pk_bf16_f32 v1, v2, v3
	v_cvt_pk_bf16_f32 v2, v4, v5
	v_cvt_pk_bf16_f32 v3, v6, v7
	v_mov_b32_e32 v12, v9
	v_mov_b32_e32 v13, v9
	s_mov_b64 exec, s[100:101]
	global_store_dwordx4 v[168:169], v[0:3], off
	s_mov_b64 exec, -1
	v_mov_b32_e32 v6, v9
	v_mov_b32_e32 v7, v9
	v_sub_f32_e32 v1, v31, v8
	v_sub_f32_e32 v0, v30, v8
	v_sub_f32_e32 v3, v29, v8
	v_sub_f32_e32 v2, v28, v8
	v_pk_mul_f32 v[4:5], v[12:13], v[2:3]
	v_pk_mul_f32 v[0:1], v[6:7], v[0:1]
	v_sub_f32_e32 v9, v25, v8
	v_pk_fma_f32 v[2:3], v[140:141], v[0:1], v[144:145]
	v_pk_fma_f32 v[0:1], v[138:139], v[4:5], v[142:143]
	v_sub_f32_e32 v5, v27, v8
	v_sub_f32_e32 v4, v26, v8
	v_sub_f32_e32 v8, v24, v8
	v_pk_mul_f32 v[8:9], v[12:13], v[8:9]
	v_pk_mul_f32 v[4:5], v[6:7], v[4:5]
	s_and_b64 vcc, exec, s[40:41]
	v_pk_fma_f32 v[6:7], v[132:133], v[4:5], v[136:137]
	v_pk_fma_f32 v[4:5], v[130:131], v[8:9], v[134:135]
	s_cbranch_vccnz .LBB0_203
	global_store_dwordx4 v[10:11], v[0:3], off offset:512
	global_store_dwordx4 v[10:11], v[4:7], off offset:528
; DI unsigned pk2(float lo, float hi) { f32x2 v = {lo, hi}; return __builtin_bit_cast(unsigned, __builtin_convertvector(v, bf2_t)); }
;     DI void fused(f32x4 (&acc)[2][2][4][2], const Unit& u, int wr, int wc, int fr, int fq, LAS unsigned char* lds, int wid, int lane) const {
;     ...
;         for (int ai = 0; ai < 2; ++ai)
; #pragma unroll
;             for (int m = 0; m < 4; ++m) {
;                 const int r = ai * HALF + wr * 64 + m * 16 + fr; const f32x2v sr = S[r]; const size_t off = (size_t)(u.pm * BM + r) * D + col0;
; #pragma unroll
;                 for (int bj = 0; bj < 2; ++bj) {
;                     const f32x4 o0 = (acc[ai][bj][m][0] - sr.x) * sr.y * gv[bj][0] + bv[bj][0], o1 = (acc[ai][bj][m][1] - sr.x) * sr.y * gv[bj][1] + bv[bj][1];
;                     if (Xo) { *(f32x4*)(Xo + off + bj * HALF) = o0; *(f32x4*)(Xo + off + bj * HALF + 4) = o1; }
;                     u32x4 w; w.x = pk2(o0[0], o0[1]); w.y = pk2(o0[2], o0[3]); w.z = pk2(o1[0], o1[1]); w.w = pk2(o1[2], o1[3]);
;                     *(u32x4*)(XB + off + bj * HALF) = w;
;                 }
;             }
.LBB0_203:
	ds_read_b64 v[8:9], v96 offset:8448
	v_cvt_pk_bf16_f32 v0, v0, v1
	v_cvt_pk_bf16_f32 v1, v2, v3
	v_cvt_pk_bf16_f32 v2, v4, v5
	v_cvt_pk_bf16_f32 v3, v6, v7
	s_mov_b64 exec, s[100:101]
	global_store_dwordx4 v[168:169], v[0:3], off offset:256
	s_mov_b64 exec, -1
	s_waitcnt lgkmcnt(0)
	v_sub_f32_e32 v7, v33, v8
	v_sub_f32_e32 v6, v32, v8
	v_add3_u32 v0, s12, v216, 32
	v_ashrrev_i32_e32 v1, 31, v0
	v_lshlrev_b64 v[0:1], 11, v[0:1]
	v_lshl_add_u64 v[10:11], v[0:1], 0, v[164:165]
	v_sub_f32_e32 v1, v39, v8
	v_sub_f32_e32 v0, v38, v8
	v_sub_f32_e32 v3, v37, v8
	v_sub_f32_e32 v2, v36, v8
	v_pk_mul_f32 v[4:5], v[8:9], v[2:3] op_sel:[1,0]
	v_pk_mul_f32 v[0:1], v[8:9], v[0:1] op_sel:[1,0]
	v_pk_mul_f32 v[12:13], v[8:9], v[6:7] op_sel:[1,0]
	v_pk_fma_f32 v[2:3], v[156:157], v[0:1], v[160:161]
	v_pk_fma_f32 v[0:1], v[154:155], v[4:5], v[158:159]
	v_sub_f32_e32 v5, v35, v8
	v_sub_f32_e32 v4, v34, v8
	v_pk_mul_f32 v[4:5], v[8:9], v[4:5] op_sel:[1,0]
	s_and_b64 vcc, exec, s[40:41]
	v_pk_fma_f32 v[6:7], v[148:149], v[4:5], v[152:153]
	v_pk_fma_f32 v[4:5], v[146:147], v[12:13], v[150:151]
	v_lshl_add_u64 v[10:11], v[10:11], 2, s[0:1]
	s_cbranch_vccnz .LBB0_205
	global_store_dwordx4 v[10:11], v[0:3], off
	global_store_dwordx4 v[10:11], v[4:7], off offset:16
.LBB0_205:
	s_nop 0
	v_cvt_pk_bf16_f32 v0, v0, v1
	v_cvt_pk_bf16_f32 v1, v2, v3
	v_cvt_pk_bf16_f32 v2, v4, v5
	v_cvt_pk_bf16_f32 v3, v6, v7
	v_mov_b32_e32 v12, v9
	v_mov_b32_e32 v13, v9
	s_mov_b64 exec, s[100:101]
	global_store_dwordx4 v[170:171], v[0:3], off
	s_mov_b64 exec, -1
	v_mov_b32_e32 v6, v9
	v_mov_b32_e32 v7, v9
	v_sub_f32_e32 v1, v47, v8
	v_sub_f32_e32 v0, v46, v8
	v_sub_f32_e32 v3, v45, v8
	v_sub_f32_e32 v2, v44, v8
	v_pk_mul_f32 v[4:5], v[12:13], v[2:3]
	v_pk_mul_f32 v[0:1], v[6:7], v[0:1]
	v_sub_f32_e32 v9, v41, v8
	v_pk_fma_f32 v[2:3], v[140:141], v[0:1], v[144:145]
	v_pk_fma_f32 v[0:1], v[138:139], v[4:5], v[142:143]
	v_sub_f32_e32 v5, v43, v8
	v_sub_f32_e32 v4, v42, v8
	v_sub_f32_e32 v8, v40, v8
	v_pk_mul_f32 v[8:9], v[12:13], v[8:9]
	v_pk_mul_f32 v[4:5], v[6:7], v[4:5]
	s_and_b64 vcc, exec, s[40:41]
	v_pk_fma_f32 v[6:7], v[132:133], v[4:5], v[136:137]
	v_pk_fma_f32 v[4:5], v[130:131], v[8:9], v[134:135]
	s_cbranch_vccnz .LBB0_207
	global_store_dwordx4 v[10:11], v[0:3], off offset:512
	global_store_dwordx4 v[10:11], v[4:7], off offset:528
.LBB0_207:
	ds_read_b64 v[8:9], v96 offset:8576
	v_cvt_pk_bf16_f32 v0, v0, v1
	v_cvt_pk_bf16_f32 v1, v2, v3
	v_cvt_pk_bf16_f32 v2, v4, v5
	v_cvt_pk_bf16_f32 v3, v6, v7
	s_mov_b64 exec, s[100:101]
	global_store_dwordx4 v[170:171], v[0:3], off offset:256
	s_mov_b64 exec, -1
	s_waitcnt lgkmcnt(0)
	v_sub_f32_e32 v7, v49, v8
	v_sub_f32_e32 v6, v48, v8
	v_add3_u32 v0, s12, v216, 48
	v_ashrrev_i32_e32 v1, 31, v0
	v_lshlrev_b64 v[0:1], 11, v[0:1]
	v_lshl_add_u64 v[10:11], v[0:1], 0, v[164:165]
	v_sub_f32_e32 v1, v55, v8
	v_sub_f32_e32 v0, v54, v8
	v_sub_f32_e32 v3, v53, v8
	v_sub_f32_e32 v2, v52, v8
	v_pk_mul_f32 v[4:5], v[8:9], v[2:3] op_sel:[1,0]
	v_pk_mul_f32 v[0:1], v[8:9], v[0:1] op_sel:[1,0]
	v_pk_mul_f32 v[12:13], v[8:9], v[6:7] op_sel:[1,0]
	v_pk_fma_f32 v[2:3], v[156:157], v[0:1], v[160:161]
	v_pk_fma_f32 v[0:1], v[154:155], v[4:5], v[158:159]
	v_sub_f32_e32 v5, v51, v8
	v_sub_f32_e32 v4, v50, v8
	v_pk_mul_f32 v[4:5], v[8:9], v[4:5] op_sel:[1,0]
	s_and_b64 vcc, exec, s[40:41]
	v_pk_fma_f32 v[6:7], v[148:149], v[4:5], v[152:153]
	v_pk_fma_f32 v[4:5], v[146:147], v[12:13], v[150:151]
	v_lshl_add_u64 v[10:11], v[10:11], 2, s[0:1]
	s_cbranch_vccnz .LBB0_209
	global_store_dwordx4 v[10:11], v[0:3], off
	global_store_dwordx4 v[10:11], v[4:7], off offset:16
.LBB0_209:
	s_nop 0
	v_cvt_pk_bf16_f32 v0, v0, v1
	v_cvt_pk_bf16_f32 v1, v2, v3
	v_cvt_pk_bf16_f32 v2, v4, v5
	v_cvt_pk_bf16_f32 v3, v6, v7
	v_mov_b32_e32 v12, v9
	v_mov_b32_e32 v13, v9
	s_mov_b64 exec, s[100:101]
	global_store_dwordx4 v[172:173], v[0:3], off
	s_mov_b64 exec, -1
	v_mov_b32_e32 v6, v9
	v_mov_b32_e32 v7, v9
	v_sub_f32_e32 v1, v63, v8
	v_sub_f32_e32 v0, v62, v8
	v_sub_f32_e32 v3, v61, v8
	v_sub_f32_e32 v2, v60, v8
	v_pk_mul_f32 v[4:5], v[12:13], v[2:3]
	v_pk_mul_f32 v[0:1], v[6:7], v[0:1]
	v_sub_f32_e32 v9, v57, v8
	v_pk_fma_f32 v[2:3], v[140:141], v[0:1], v[144:145]
	v_pk_fma_f32 v[0:1], v[138:139], v[4:5], v[142:143]
	v_sub_f32_e32 v5, v59, v8
	v_sub_f32_e32 v4, v58, v8
	v_sub_f32_e32 v8, v56, v8
	v_pk_mul_f32 v[8:9], v[12:13], v[8:9]
	v_pk_mul_f32 v[4:5], v[6:7], v[4:5]
	s_and_b64 vcc, exec, s[40:41]
	v_pk_fma_f32 v[6:7], v[132:133], v[4:5], v[136:137]
	v_pk_fma_f32 v[4:5], v[130:131], v[8:9], v[134:135]
	s_cbranch_vccnz .LBB0_211
	global_store_dwordx4 v[10:11], v[0:3], off offset:512
	global_store_dwordx4 v[10:11], v[4:7], off offset:528
.LBB0_211:
	ds_read_b64 v[8:9], v96 offset:9216
	v_cvt_pk_bf16_f32 v0, v0, v1
	v_cvt_pk_bf16_f32 v1, v2, v3
	v_cvt_pk_bf16_f32 v2, v4, v5
	v_cvt_pk_bf16_f32 v3, v6, v7
	s_mov_b64 exec, s[100:101]
	global_store_dwordx4 v[172:173], v[0:3], off offset:256
	s_mov_b64 exec, -1
	s_waitcnt lgkmcnt(0)
	v_sub_f32_e32 v7, v65, v8
	v_sub_f32_e32 v6, v64, v8
	v_add_u32_e32 v0, 0x80, v182
	v_ashrrev_i32_e32 v1, 31, v0
	v_lshlrev_b64 v[0:1], 11, v[0:1]
	v_lshl_add_u64 v[10:11], v[0:1], 0, v[164:165]
	v_sub_f32_e32 v1, v71, v8
	v_sub_f32_e32 v0, v70, v8
	v_sub_f32_e32 v3, v69, v8
	v_sub_f32_e32 v2, v68, v8
	v_pk_mul_f32 v[4:5], v[8:9], v[2:3] op_sel:[1,0]
	v_pk_mul_f32 v[0:1], v[8:9], v[0:1] op_sel:[1,0]
	v_pk_mul_f32 v[12:13], v[8:9], v[6:7] op_sel:[1,0]
	v_pk_fma_f32 v[2:3], v[156:157], v[0:1], v[160:161]
	v_pk_fma_f32 v[0:1], v[154:155], v[4:5], v[158:159]
	v_sub_f32_e32 v5, v67, v8
	v_sub_f32_e32 v4, v66, v8
	v_pk_mul_f32 v[4:5], v[8:9], v[4:5] op_sel:[1,0]
	s_and_b64 vcc, exec, s[40:41]
	v_pk_fma_f32 v[6:7], v[148:149], v[4:5], v[152:153]
	v_pk_fma_f32 v[4:5], v[146:147], v[12:13], v[150:151]
	v_lshl_add_u64 v[10:11], v[10:11], 2, s[0:1]
	s_cbranch_vccnz .LBB0_213
	global_store_dwordx4 v[10:11], v[0:3], off
	global_store_dwordx4 v[10:11], v[4:7], off offset:16
; DI unsigned pk2(float lo, float hi) { f32x2 v = {lo, hi}; return __builtin_bit_cast(unsigned, __builtin_convertvector(v, bf2_t)); }
;     DI void fused(f32x4 (&acc)[2][2][4][2], const Unit& u, int wr, int wc, int fr, int fq, LAS unsigned char* lds, int wid, int lane) const {
;     ...
;         for (int ai = 0; ai < 2; ++ai)
; #pragma unroll
;             for (int m = 0; m < 4; ++m) {
;                 const int r = ai * HALF + wr * 64 + m * 16 + fr; const f32x2v sr = S[r]; const size_t off = (size_t)(u.pm * BM + r) * D + col0;
; #pragma unroll
;                 for (int bj = 0; bj < 2; ++bj) {
;                     const f32x4 o0 = (acc[ai][bj][m][0] - sr.x) * sr.y * gv[bj][0] + bv[bj][0], o1 = (acc[ai][bj][m][1] - sr.x) * sr.y * gv[bj][1] + bv[bj][1];
;                     if (Xo) { *(f32x4*)(Xo + off + bj * HALF) = o0; *(f32x4*)(Xo + off + bj * HALF + 4) = o1; }
;                     u32x4 w; w.x = pk2(o0[0], o0[1]); w.y = pk2(o0[2], o0[3]); w.z = pk2(o1[0], o1[1]); w.w = pk2(o1[2], o1[3]);
;                     *(u32x4*)(XB + off + bj * HALF) = w;
;                 }
;             }
.LBB0_213:
	s_nop 0
	v_cvt_pk_bf16_f32 v0, v0, v1
	v_cvt_pk_bf16_f32 v1, v2, v3
	v_cvt_pk_bf16_f32 v2, v4, v5
	v_cvt_pk_bf16_f32 v3, v6, v7
	v_mov_b32_e32 v12, v9
	v_mov_b32_e32 v13, v9
	s_mov_b64 exec, s[100:101]
	global_store_dwordx4 v[174:175], v[0:3], off
	s_mov_b64 exec, -1
	v_mov_b32_e32 v6, v9
	v_mov_b32_e32 v7, v9
	v_sub_f32_e32 v1, v79, v8
	v_sub_f32_e32 v0, v78, v8
	v_sub_f32_e32 v3, v77, v8
	v_sub_f32_e32 v2, v76, v8
	v_pk_mul_f32 v[4:5], v[12:13], v[2:3]
	v_pk_mul_f32 v[0:1], v[6:7], v[0:1]
	v_sub_f32_e32 v9, v73, v8
	v_pk_fma_f32 v[2:3], v[140:141], v[0:1], v[144:145]
	v_pk_fma_f32 v[0:1], v[138:139], v[4:5], v[142:143]
	v_sub_f32_e32 v5, v75, v8
	v_sub_f32_e32 v4, v74, v8
	v_sub_f32_e32 v8, v72, v8
	v_pk_mul_f32 v[8:9], v[12:13], v[8:9]
	v_pk_mul_f32 v[4:5], v[6:7], v[4:5]
	s_and_b64 vcc, exec, s[40:41]
	v_pk_fma_f32 v[6:7], v[132:133], v[4:5], v[136:137]
	v_pk_fma_f32 v[4:5], v[130:131], v[8:9], v[134:135]
	s_cbranch_vccnz .LBB0_215
	global_store_dwordx4 v[10:11], v[0:3], off offset:512
	global_store_dwordx4 v[10:11], v[4:7], off offset:528
.LBB0_215:
	ds_read_b64 v[8:9], v96 offset:9344
	v_cvt_pk_bf16_f32 v0, v0, v1
	v_cvt_pk_bf16_f32 v1, v2, v3
	v_cvt_pk_bf16_f32 v2, v4, v5
	v_cvt_pk_bf16_f32 v3, v6, v7
	s_mov_b64 exec, s[100:101]
	global_store_dwordx4 v[174:175], v[0:3], off offset:256
	s_mov_b64 exec, -1
	s_waitcnt lgkmcnt(0)
	v_sub_f32_e32 v7, v81, v8
	v_sub_f32_e32 v6, v80, v8
	v_add_u32_e32 v0, 0x90, v182
	v_ashrrev_i32_e32 v1, 31, v0
	v_lshlrev_b64 v[0:1], 11, v[0:1]
	v_lshl_add_u64 v[10:11], v[0:1], 0, v[164:165]
	v_sub_f32_e32 v1, v87, v8
	v_sub_f32_e32 v0, v86, v8
	v_sub_f32_e32 v3, v85, v8
	v_sub_f32_e32 v2, v84, v8
	v_pk_mul_f32 v[4:5], v[8:9], v[2:3] op_sel:[1,0]
	v_pk_mul_f32 v[0:1], v[8:9], v[0:1] op_sel:[1,0]
	v_pk_mul_f32 v[12:13], v[8:9], v[6:7] op_sel:[1,0]
	v_pk_fma_f32 v[2:3], v[156:157], v[0:1], v[160:161]
	v_pk_fma_f32 v[0:1], v[154:155], v[4:5], v[158:159]
	v_sub_f32_e32 v5, v83, v8
	v_sub_f32_e32 v4, v82, v8
	v_pk_mul_f32 v[4:5], v[8:9], v[4:5] op_sel:[1,0]
	s_and_b64 vcc, exec, s[40:41]
	v_pk_fma_f32 v[6:7], v[148:149], v[4:5], v[152:153]
	v_pk_fma_f32 v[4:5], v[146:147], v[12:13], v[150:151]
	v_lshl_add_u64 v[10:11], v[10:11], 2, s[0:1]
	s_cbranch_vccnz .LBB0_217
	global_store_dwordx4 v[10:11], v[0:3], off
	global_store_dwordx4 v[10:11], v[4:7], off offset:16
.LBB0_217:
	s_nop 0
	v_cvt_pk_bf16_f32 v0, v0, v1
	v_cvt_pk_bf16_f32 v1, v2, v3
	v_cvt_pk_bf16_f32 v2, v4, v5
	v_cvt_pk_bf16_f32 v3, v6, v7
	v_mov_b32_e32 v12, v9
	v_mov_b32_e32 v13, v9
	s_mov_b64 exec, s[100:101]
	global_store_dwordx4 v[176:177], v[0:3], off
	s_mov_b64 exec, -1
	v_mov_b32_e32 v6, v9
	v_mov_b32_e32 v7, v9
	v_sub_f32_e32 v1, v95, v8
	v_sub_f32_e32 v0, v94, v8
	v_sub_f32_e32 v3, v93, v8
	v_sub_f32_e32 v2, v92, v8
	v_pk_mul_f32 v[4:5], v[12:13], v[2:3]
	v_pk_mul_f32 v[0:1], v[6:7], v[0:1]
	v_sub_f32_e32 v9, v89, v8
	v_pk_fma_f32 v[2:3], v[140:141], v[0:1], v[144:145]
	v_pk_fma_f32 v[0:1], v[138:139], v[4:5], v[142:143]
	v_sub_f32_e32 v5, v91, v8
	v_sub_f32_e32 v4, v90, v8
	v_sub_f32_e32 v8, v88, v8
	v_pk_mul_f32 v[8:9], v[12:13], v[8:9]
	v_pk_mul_f32 v[4:5], v[6:7], v[4:5]
	s_and_b64 vcc, exec, s[40:41]
	v_pk_fma_f32 v[6:7], v[132:133], v[4:5], v[136:137]
	v_pk_fma_f32 v[4:5], v[130:131], v[8:9], v[134:135]
	s_cbranch_vccnz .LBB0_219
	global_store_dwordx4 v[10:11], v[0:3], off offset:512
	global_store_dwordx4 v[10:11], v[4:7], off offset:528
.LBB0_219:
	ds_read_b64 v[8:9], v96 offset:9472
	v_cvt_pk_bf16_f32 v0, v0, v1
	v_cvt_pk_bf16_f32 v1, v2, v3
	v_cvt_pk_bf16_f32 v2, v4, v5
	v_cvt_pk_bf16_f32 v3, v6, v7
	s_mov_b64 exec, s[100:101]
	global_store_dwordx4 v[176:177], v[0:3], off offset:256
	s_mov_b64 exec, -1
	s_waitcnt lgkmcnt(0)
	v_sub_f32_e32 v7, v107, v8
	v_sub_f32_e32 v6, v106, v8
	v_add_u32_e32 v0, 0xa0, v182
	v_ashrrev_i32_e32 v1, 31, v0
	v_lshlrev_b64 v[0:1], 11, v[0:1]
	v_lshl_add_u64 v[10:11], v[0:1], 0, v[164:165]
	v_sub_f32_e32 v1, v117, v8
	v_sub_f32_e32 v0, v116, v8
	v_sub_f32_e32 v3, v115, v8
	v_sub_f32_e32 v2, v114, v8
	v_pk_mul_f32 v[4:5], v[8:9], v[2:3] op_sel:[1,0]
	v_pk_mul_f32 v[0:1], v[8:9], v[0:1] op_sel:[1,0]
	v_pk_mul_f32 v[12:13], v[8:9], v[6:7] op_sel:[1,0]
	v_pk_fma_f32 v[2:3], v[156:157], v[0:1], v[160:161]
	v_pk_fma_f32 v[0:1], v[154:155], v[4:5], v[158:159]
	v_sub_f32_e32 v5, v109, v8
	v_sub_f32_e32 v4, v108, v8
	v_pk_mul_f32 v[4:5], v[8:9], v[4:5] op_sel:[1,0]
	s_and_b64 vcc, exec, s[40:41]
	v_pk_fma_f32 v[6:7], v[148:149], v[4:5], v[152:153]
	v_pk_fma_f32 v[4:5], v[146:147], v[12:13], v[150:151]
	v_lshl_add_u64 v[10:11], v[10:11], 2, s[0:1]
	s_cbranch_vccnz .LBB0_221
	global_store_dwordx4 v[10:11], v[0:3], off
	global_store_dwordx4 v[10:11], v[4:7], off offset:16
; DI unsigned pk2(float lo, float hi) { f32x2 v = {lo, hi}; return __builtin_bit_cast(unsigned, __builtin_convertvector(v, bf2_t)); }
;     DI void fused(f32x4 (&acc)[2][2][4][2], const Unit& u, int wr, int wc, int fr, int fq, LAS unsigned char* lds, int wid, int lane) const {
;     ...
;         for (int ai = 0; ai < 2; ++ai)
; #pragma unroll
;             for (int m = 0; m < 4; ++m) {
;                 const int r = ai * HALF + wr * 64 + m * 16 + fr; const f32x2v sr = S[r]; const size_t off = (size_t)(u.pm * BM + r) * D + col0;
; #pragma unroll
;                 for (int bj = 0; bj < 2; ++bj) {
;                     const f32x4 o0 = (acc[ai][bj][m][0] - sr.x) * sr.y * gv[bj][0] + bv[bj][0], o1 = (acc[ai][bj][m][1] - sr.x) * sr.y * gv[bj][1] + bv[bj][1];
;                     if (Xo) { *(f32x4*)(Xo + off + bj * HALF) = o0; *(f32x4*)(Xo + off + bj * HALF + 4) = o1; }
;                     u32x4 w; w.x = pk2(o0[0], o0[1]); w.y = pk2(o0[2], o0[3]); w.z = pk2(o1[0], o1[1]); w.w = pk2(o1[2], o1[3]);
;                     *(u32x4*)(XB + off + bj * HALF) = w;
;                 }
;             }
.LBB0_221:
	s_nop 0
	v_cvt_pk_bf16_f32 v0, v0, v1
	v_cvt_pk_bf16_f32 v1, v2, v3
	v_cvt_pk_bf16_f32 v2, v4, v5
	v_cvt_pk_bf16_f32 v3, v6, v7
	v_mov_b32_e32 v12, v9
	v_mov_b32_e32 v13, v9
	s_mov_b64 exec, s[100:101]
	global_store_dwordx4 v[178:179], v[0:3], off
	s_mov_b64 exec, -1
	v_mov_b32_e32 v6, v9
	v_mov_b32_e32 v7, v9
	v_sub_f32_e32 v1, v129, v8
	v_sub_f32_e32 v0, v128, v8
	v_sub_f32_e32 v3, v127, v8
	v_sub_f32_e32 v2, v126, v8
	v_pk_mul_f32 v[4:5], v[12:13], v[2:3]
	v_pk_mul_f32 v[0:1], v[6:7], v[0:1]
	v_sub_f32_e32 v9, v123, v8
	v_pk_fma_f32 v[2:3], v[140:141], v[0:1], v[144:145]
	v_pk_fma_f32 v[0:1], v[138:139], v[4:5], v[142:143]
	v_sub_f32_e32 v5, v125, v8
	v_sub_f32_e32 v4, v124, v8
	v_sub_f32_e32 v8, v122, v8
	v_pk_mul_f32 v[8:9], v[12:13], v[8:9]
	v_pk_mul_f32 v[4:5], v[6:7], v[4:5]
	s_and_b64 vcc, exec, s[40:41]
	v_pk_fma_f32 v[6:7], v[132:133], v[4:5], v[136:137]
	v_pk_fma_f32 v[4:5], v[130:131], v[8:9], v[134:135]
	s_cbranch_vccnz .LBB0_223
	global_store_dwordx4 v[10:11], v[0:3], off offset:512
	global_store_dwordx4 v[10:11], v[4:7], off offset:528
.LBB0_223:
	ds_read_b64 v[8:9], v96 offset:9600
	v_cvt_pk_bf16_f32 v0, v0, v1
	v_cvt_pk_bf16_f32 v1, v2, v3
	v_cvt_pk_bf16_f32 v2, v4, v5
	v_cvt_pk_bf16_f32 v3, v6, v7
	s_mov_b64 exec, s[100:101]
	global_store_dwordx4 v[178:179], v[0:3], off offset:256
	s_mov_b64 exec, -1
	s_waitcnt lgkmcnt(0)
	v_sub_f32_e32 v7, v111, v8
	v_sub_f32_e32 v6, v110, v8
	v_add_u32_e32 v0, 0xb0, v182
	v_ashrrev_i32_e32 v1, 31, v0
	v_lshlrev_b64 v[0:1], 11, v[0:1]
	v_lshl_add_u64 v[10:11], v[0:1], 0, v[164:165]
	v_sub_f32_e32 v1, v121, v8
	v_sub_f32_e32 v0, v120, v8
	v_sub_f32_e32 v3, v119, v8
	v_sub_f32_e32 v2, v118, v8
	v_pk_mul_f32 v[4:5], v[8:9], v[2:3] op_sel:[1,0]
	v_pk_mul_f32 v[0:1], v[8:9], v[0:1] op_sel:[1,0]
	v_pk_mul_f32 v[12:13], v[8:9], v[6:7] op_sel:[1,0]
	v_pk_fma_f32 v[2:3], v[156:157], v[0:1], v[160:161]
	v_pk_fma_f32 v[0:1], v[154:155], v[4:5], v[158:159]
	v_sub_f32_e32 v5, v113, v8
	v_sub_f32_e32 v4, v112, v8
	v_pk_mul_f32 v[4:5], v[8:9], v[4:5] op_sel:[1,0]
	s_and_b64 vcc, exec, s[40:41]
	v_pk_fma_f32 v[6:7], v[148:149], v[4:5], v[152:153]
	v_pk_fma_f32 v[4:5], v[146:147], v[12:13], v[150:151]
	v_lshl_add_u64 v[10:11], v[10:11], 2, s[0:1]
	s_cbranch_vccnz .LBB0_225
	global_store_dwordx4 v[10:11], v[0:3], off
	global_store_dwordx4 v[10:11], v[4:7], off offset:16
.LBB0_225:
	s_nop 0
	v_cvt_pk_bf16_f32 v0, v0, v1
	v_cvt_pk_bf16_f32 v1, v2, v3
	v_cvt_pk_bf16_f32 v2, v4, v5
	v_cvt_pk_bf16_f32 v3, v6, v7
	v_mov_b32_e32 v12, v9
	v_mov_b32_e32 v13, v9
	s_mov_b64 exec, s[100:101]
	global_store_dwordx4 v[180:181], v[0:3], off
	s_mov_b64 exec, -1
	v_mov_b32_e32 v6, v9
	v_mov_b32_e32 v7, v9
	v_sub_f32_e32 v1, v105, v8
	v_sub_f32_e32 v0, v104, v8
	v_sub_f32_e32 v3, v103, v8
	v_sub_f32_e32 v2, v102, v8
	v_pk_mul_f32 v[4:5], v[12:13], v[2:3]
	v_pk_mul_f32 v[0:1], v[6:7], v[0:1]
	v_sub_f32_e32 v9, v99, v8
	v_pk_fma_f32 v[2:3], v[140:141], v[0:1], v[144:145]
	v_pk_fma_f32 v[0:1], v[138:139], v[4:5], v[142:143]
	v_sub_f32_e32 v5, v101, v8
	v_sub_f32_e32 v4, v100, v8
	v_sub_f32_e32 v8, v98, v8
	v_pk_mul_f32 v[8:9], v[12:13], v[8:9]
	v_pk_mul_f32 v[4:5], v[6:7], v[4:5]
	s_and_b64 vcc, exec, s[40:41]
	v_pk_fma_f32 v[6:7], v[132:133], v[4:5], v[136:137]
	v_pk_fma_f32 v[4:5], v[130:131], v[8:9], v[134:135]
	s_cbranch_vccnz .LBB0_227
	global_store_dwordx4 v[10:11], v[0:3], off offset:512
	global_store_dwordx4 v[10:11], v[4:7], off offset:528
.LBB0_227:
	s_nop 0
	v_cvt_pk_bf16_f32 v0, v0, v1
	v_cvt_pk_bf16_f32 v1, v2, v3
	v_cvt_pk_bf16_f32 v2, v4, v5
	v_cvt_pk_bf16_f32 v3, v6, v7
	s_mov_b64 exec, s[100:101]
	global_store_dwordx4 v[180:181], v[0:3], off offset:256
	s_mov_b64 exec, -1
